# H (SwiGLU output) stored write-through (sc1) on top of v22
# speedup vs baseline: 1.0064x; 1.0064x over previous
; __device__ __forceinline__ unsigned cvt_pk_bf16(float lo, float hi) { unsigned r; asm volatile("v_cvt_pk_bf16_f32 %0, %1, %2" : "=v"(r) : "v"(lo), "v"(hi)); return r; }
; __device__ __forceinline__ float silu_f(float g) { return g * __builtin_amdgcn_rcpf(1.0f + __expf(-g)); }
;     __device__ __forceinline__ void operator()(const f32x4 (&acc)[2][2][4][2], const Unit& u, int ui, int wr, int wc, int fr, int fq) const {
;         const int row0 = u.pm * BM + wr * 64 + fr, col0 = u.pn * HALF + wc * 32 + 8 * fq;
; #pragma unroll
;         for (int ai = 0; ai < 2; ++ai)
; #pragma unroll
;             for (int m = 0; m < 4; ++m) {
;                 const int row = row0 + ai * HALF + m * 16;
;                 const float s = rsb[(ui & 1) * 256 + ai * HALF + wr * 64 + m * 16 + fr];
;                 f32x4 g0 = acc[ai][0][m][0] * s, g1 = acc[ai][0][m][1] * s, u0 = acc[ai][1][m][0] * s, u1 = acc[ai][1][m][1] * s;
;                 u32x4 w;
;                 w.x = cvt_pk_bf16(silu_f(g0[0]) * u0[0], silu_f(g0[1]) * u0[1]); w.y = cvt_pk_bf16(silu_f(g0[2]) * u0[2], silu_f(g0[3]) * u0[3]);
;                 w.z = cvt_pk_bf16(silu_f(g1[0]) * u1[0], silu_f(g1[1]) * u1[1]); w.w = cvt_pk_bf16(silu_f(g1[2]) * u1[2], silu_f(g1[3]) * u1[3]);
;                 *(u32x4*)(H + (size_t)row * ldh + col0) = w;
;             }
;     }
.LBB0_128:
	s_lshl_b32 s2, s61, 10
	s_and_b32 s2, s2, 0x400
	v_add_u32_e32 v165, s2, v162
	ds_read_b32 v176, v165
	ds_read_b32 v178, v165 offset:64
	ds_read_b32 v180, v165 offset:128
	ds_read_b32 v182, v165 offset:192
	ds_read_b32 v184, v165 offset:512
	ds_read_b32 v186, v165 offset:576
	ds_read_b32 v188, v165 offset:640
	ds_read_b32 v190, v165 offset:704
	v_lshl_or_b32 v158, s45, 7, v161
	v_lshl_add_u32 v164, s44, 8, v1
	v_ashrrev_i32_e32 v159, 31, v158
	s_mov_b32 s98, 0x16000
	s_mov_b32 s99, 0
	s_mov_b32 s100, 0x6e000
	s_mov_b32 s101, 0
	v_mov_b32_e32 v172, 0xbfb8aa3b
	v_mov_b32_e32 v174, 1.0
	v_mov_b64_e32 v[166:167], s[8:9]
	v_mad_i64_i32 v[192:193], s[2:3], v164, s71, v[166:167]
	v_lshlrev_b64 v[166:167], 1, v[158:159]
	v_lshl_add_u64 v[192:193], v[192:193], 0, v[166:167]
	s_waitcnt lgkmcnt(0)
	v_pk_mul_f32 v[142:143], v[142:143], v[176:177] op_sel_hi:[1,0]
	v_pk_mul_f32 v[144:145], v[144:145], v[176:177] op_sel_hi:[1,0]
	v_pk_mul_f32 v[138:139], v[138:139], v[176:177] op_sel_hi:[1,0]
	v_pk_mul_f32 v[140:141], v[140:141], v[176:177] op_sel_hi:[1,0]
	v_pk_mul_f32 v[134:135], v[134:135], v[176:177] op_sel_hi:[1,0]
	v_pk_mul_f32 v[136:137], v[136:137], v[176:177] op_sel_hi:[1,0]
	v_pk_mul_f32 v[130:131], v[130:131], v[176:177] op_sel_hi:[1,0]
	v_pk_mul_f32 v[132:133], v[132:133], v[176:177] op_sel_hi:[1,0]
	v_pk_mul_f32 v[168:169], v[142:143], v[172:173] op_sel_hi:[1,0]
	v_pk_mul_f32 v[170:171], v[144:145], v[172:173] op_sel_hi:[1,0]
	v_exp_f32_e32 v168, v168
	v_exp_f32_e32 v169, v169
	v_exp_f32_e32 v170, v170
	v_exp_f32_e32 v171, v171
	v_pk_add_f32 v[168:169], v[168:169], v[174:175] op_sel_hi:[1,0]
	v_pk_add_f32 v[170:171], v[170:171], v[174:175] op_sel_hi:[1,0]
	v_rcp_f32_e32 v168, v168
	v_rcp_f32_e32 v169, v169
	v_rcp_f32_e32 v170, v170
	v_rcp_f32_e32 v171, v171
	v_pk_mul_f32 v[142:143], v[142:143], v[168:169]
	v_pk_mul_f32 v[144:145], v[144:145], v[170:171]
	v_pk_mul_f32 v[134:135], v[134:135], v[142:143]
	v_pk_mul_f32 v[136:137], v[136:137], v[144:145]
	v_cvt_pk_bf16_f32 v134, v134, v135
	v_cvt_pk_bf16_f32 v135, v136, v137
	v_pk_mul_f32 v[168:169], v[138:139], v[172:173] op_sel_hi:[1,0]
	v_pk_mul_f32 v[170:171], v[140:141], v[172:173] op_sel_hi:[1,0]
	v_exp_f32_e32 v168, v168
	v_exp_f32_e32 v169, v169
	v_exp_f32_e32 v170, v170
	v_exp_f32_e32 v171, v171
	v_pk_add_f32 v[168:169], v[168:169], v[174:175] op_sel_hi:[1,0]
	v_pk_add_f32 v[170:171], v[170:171], v[174:175] op_sel_hi:[1,0]
	v_rcp_f32_e32 v168, v168
	v_rcp_f32_e32 v169, v169
	v_rcp_f32_e32 v170, v170
	v_rcp_f32_e32 v171, v171
	v_pk_mul_f32 v[138:139], v[138:139], v[168:169]
	v_pk_mul_f32 v[140:141], v[140:141], v[170:171]
	v_pk_mul_f32 v[130:131], v[130:131], v[138:139]
	v_pk_mul_f32 v[132:133], v[132:133], v[140:141]
	v_cvt_pk_bf16_f32 v136, v130, v131
	v_cvt_pk_bf16_f32 v137, v132, v133
	global_store_dwordx4 v[192:193], v[134:137], off sc1
	v_lshl_add_u64 v[192:193], v[192:193], 0, s[98:99]
	v_pk_mul_f32 v[126:127], v[126:127], v[178:179] op_sel_hi:[1,0]
	v_pk_mul_f32 v[128:129], v[128:129], v[178:179] op_sel_hi:[1,0]
	v_pk_mul_f32 v[122:123], v[122:123], v[178:179] op_sel_hi:[1,0]
	v_pk_mul_f32 v[124:125], v[124:125], v[178:179] op_sel_hi:[1,0]
	v_pk_mul_f32 v[118:119], v[118:119], v[178:179] op_sel_hi:[1,0]
	v_pk_mul_f32 v[120:121], v[120:121], v[178:179] op_sel_hi:[1,0]
	v_pk_mul_f32 v[114:115], v[114:115], v[178:179] op_sel_hi:[1,0]
	v_pk_mul_f32 v[116:117], v[116:117], v[178:179] op_sel_hi:[1,0]
	v_pk_mul_f32 v[168:169], v[126:127], v[172:173] op_sel_hi:[1,0]
	v_pk_mul_f32 v[170:171], v[128:129], v[172:173] op_sel_hi:[1,0]
	v_exp_f32_e32 v168, v168
	v_exp_f32_e32 v169, v169
	v_exp_f32_e32 v170, v170
	v_exp_f32_e32 v171, v171
	v_pk_add_f32 v[168:169], v[168:169], v[174:175] op_sel_hi:[1,0]
	v_pk_add_f32 v[170:171], v[170:171], v[174:175] op_sel_hi:[1,0]
	v_rcp_f32_e32 v168, v168
	v_rcp_f32_e32 v169, v169
	v_rcp_f32_e32 v170, v170
	v_rcp_f32_e32 v171, v171
	v_pk_mul_f32 v[126:127], v[126:127], v[168:169]
	v_pk_mul_f32 v[128:129], v[128:129], v[170:171]
	v_pk_mul_f32 v[118:119], v[118:119], v[126:127]
	v_pk_mul_f32 v[120:121], v[120:121], v[128:129]
	v_cvt_pk_bf16_f32 v118, v118, v119
	v_cvt_pk_bf16_f32 v119, v120, v121
	v_pk_mul_f32 v[168:169], v[122:123], v[172:173] op_sel_hi:[1,0]
	v_pk_mul_f32 v[170:171], v[124:125], v[172:173] op_sel_hi:[1,0]
	v_exp_f32_e32 v168, v168
	v_exp_f32_e32 v169, v169
	v_exp_f32_e32 v170, v170
	v_exp_f32_e32 v171, v171
	v_pk_add_f32 v[168:169], v[168:169], v[174:175] op_sel_hi:[1,0]
	v_pk_add_f32 v[170:171], v[170:171], v[174:175] op_sel_hi:[1,0]
	v_rcp_f32_e32 v168, v168
	v_rcp_f32_e32 v169, v169
	v_rcp_f32_e32 v170, v170
	v_rcp_f32_e32 v171, v171
	v_pk_mul_f32 v[122:123], v[122:123], v[168:169]
	v_pk_mul_f32 v[124:125], v[124:125], v[170:171]
	v_pk_mul_f32 v[114:115], v[114:115], v[122:123]
	v_pk_mul_f32 v[116:117], v[116:117], v[124:125]
	v_cvt_pk_bf16_f32 v120, v114, v115
	v_cvt_pk_bf16_f32 v121, v116, v117
	global_store_dwordx4 v[192:193], v[118:121], off sc1
	v_lshl_add_u64 v[192:193], v[192:193], 0, s[98:99]
	v_pk_mul_f32 v[110:111], v[110:111], v[180:181] op_sel_hi:[1,0]
	v_pk_mul_f32 v[112:113], v[112:113], v[180:181] op_sel_hi:[1,0]
	v_pk_mul_f32 v[106:107], v[106:107], v[180:181] op_sel_hi:[1,0]
	v_pk_mul_f32 v[108:109], v[108:109], v[180:181] op_sel_hi:[1,0]
	v_pk_mul_f32 v[102:103], v[102:103], v[180:181] op_sel_hi:[1,0]
	v_pk_mul_f32 v[104:105], v[104:105], v[180:181] op_sel_hi:[1,0]
	v_pk_mul_f32 v[98:99], v[98:99], v[180:181] op_sel_hi:[1,0]
	v_pk_mul_f32 v[100:101], v[100:101], v[180:181] op_sel_hi:[1,0]
	v_pk_mul_f32 v[168:169], v[110:111], v[172:173] op_sel_hi:[1,0]
	v_pk_mul_f32 v[170:171], v[112:113], v[172:173] op_sel_hi:[1,0]
; __device__ __forceinline__ unsigned cvt_pk_bf16(float lo, float hi) { unsigned r; asm volatile("v_cvt_pk_bf16_f32 %0, %1, %2" : "=v"(r) : "v"(lo), "v"(hi)); return r; }
; __device__ __forceinline__ float silu_f(float g) { return g * __builtin_amdgcn_rcpf(1.0f + __expf(-g)); }
;     __device__ __forceinline__ void operator()(const f32x4 (&acc)[2][2][4][2], const Unit& u, int ui, int wr, int wc, int fr, int fq) const {
;         const int row0 = u.pm * BM + wr * 64 + fr, col0 = u.pn * HALF + wc * 32 + 8 * fq;
; #pragma unroll
;         for (int ai = 0; ai < 2; ++ai)
; #pragma unroll
;             for (int m = 0; m < 4; ++m) {
;                 const int row = row0 + ai * HALF + m * 16;
;                 const float s = rsb[(ui & 1) * 256 + ai * HALF + wr * 64 + m * 16 + fr];
;                 f32x4 g0 = acc[ai][0][m][0] * s, g1 = acc[ai][0][m][1] * s, u0 = acc[ai][1][m][0] * s, u1 = acc[ai][1][m][1] * s;
;                 u32x4 w;
;                 w.x = cvt_pk_bf16(silu_f(g0[0]) * u0[0], silu_f(g0[1]) * u0[1]); w.y = cvt_pk_bf16(silu_f(g0[2]) * u0[2], silu_f(g0[3]) * u0[3]);
;                 w.z = cvt_pk_bf16(silu_f(g1[0]) * u1[0], silu_f(g1[1]) * u1[1]); w.w = cvt_pk_bf16(silu_f(g1[2]) * u1[2], silu_f(g1[3]) * u1[3]);
;                 *(u32x4*)(H + (size_t)row * ldh + col0) = w;
	v_exp_f32_e32 v168, v168
	v_exp_f32_e32 v169, v169
	v_exp_f32_e32 v170, v170
	v_exp_f32_e32 v171, v171
	v_pk_add_f32 v[168:169], v[168:169], v[174:175] op_sel_hi:[1,0]
	v_pk_add_f32 v[170:171], v[170:171], v[174:175] op_sel_hi:[1,0]
	v_rcp_f32_e32 v168, v168
	v_rcp_f32_e32 v169, v169
	v_rcp_f32_e32 v170, v170
	v_rcp_f32_e32 v171, v171
	v_pk_mul_f32 v[110:111], v[110:111], v[168:169]
	v_pk_mul_f32 v[112:113], v[112:113], v[170:171]
	v_pk_mul_f32 v[102:103], v[102:103], v[110:111]
	v_pk_mul_f32 v[104:105], v[104:105], v[112:113]
	v_cvt_pk_bf16_f32 v102, v102, v103
	v_cvt_pk_bf16_f32 v103, v104, v105
	v_pk_mul_f32 v[168:169], v[106:107], v[172:173] op_sel_hi:[1,0]
	v_pk_mul_f32 v[170:171], v[108:109], v[172:173] op_sel_hi:[1,0]
	v_exp_f32_e32 v168, v168
	v_exp_f32_e32 v169, v169
	v_exp_f32_e32 v170, v170
	v_exp_f32_e32 v171, v171
	v_pk_add_f32 v[168:169], v[168:169], v[174:175] op_sel_hi:[1,0]
	v_pk_add_f32 v[170:171], v[170:171], v[174:175] op_sel_hi:[1,0]
	v_rcp_f32_e32 v168, v168
	v_rcp_f32_e32 v169, v169
	v_rcp_f32_e32 v170, v170
	v_rcp_f32_e32 v171, v171
	v_pk_mul_f32 v[106:107], v[106:107], v[168:169]
	v_pk_mul_f32 v[108:109], v[108:109], v[170:171]
	v_pk_mul_f32 v[98:99], v[98:99], v[106:107]
	v_pk_mul_f32 v[100:101], v[100:101], v[108:109]
	v_cvt_pk_bf16_f32 v104, v98, v99
	v_cvt_pk_bf16_f32 v105, v100, v101
	global_store_dwordx4 v[192:193], v[102:105], off sc1
	v_lshl_add_u64 v[192:193], v[192:193], 0, s[98:99]
	v_pk_mul_f32 v[94:95], v[94:95], v[182:183] op_sel_hi:[1,0]
	v_pk_mul_f32 v[96:97], v[96:97], v[182:183] op_sel_hi:[1,0]
	v_pk_mul_f32 v[90:91], v[90:91], v[182:183] op_sel_hi:[1,0]
	v_pk_mul_f32 v[92:93], v[92:93], v[182:183] op_sel_hi:[1,0]
	v_pk_mul_f32 v[86:87], v[86:87], v[182:183] op_sel_hi:[1,0]
	v_pk_mul_f32 v[88:89], v[88:89], v[182:183] op_sel_hi:[1,0]
	v_pk_mul_f32 v[82:83], v[82:83], v[182:183] op_sel_hi:[1,0]
	v_pk_mul_f32 v[84:85], v[84:85], v[182:183] op_sel_hi:[1,0]
	v_pk_mul_f32 v[168:169], v[94:95], v[172:173] op_sel_hi:[1,0]
	v_pk_mul_f32 v[170:171], v[96:97], v[172:173] op_sel_hi:[1,0]
	v_exp_f32_e32 v168, v168
	v_exp_f32_e32 v169, v169
	v_exp_f32_e32 v170, v170
	v_exp_f32_e32 v171, v171
	v_pk_add_f32 v[168:169], v[168:169], v[174:175] op_sel_hi:[1,0]
	v_pk_add_f32 v[170:171], v[170:171], v[174:175] op_sel_hi:[1,0]
	v_rcp_f32_e32 v168, v168
	v_rcp_f32_e32 v169, v169
	v_rcp_f32_e32 v170, v170
	v_rcp_f32_e32 v171, v171
	v_pk_mul_f32 v[94:95], v[94:95], v[168:169]
	v_pk_mul_f32 v[96:97], v[96:97], v[170:171]
	v_pk_mul_f32 v[86:87], v[86:87], v[94:95]
	v_pk_mul_f32 v[88:89], v[88:89], v[96:97]
	v_cvt_pk_bf16_f32 v86, v86, v87
	v_cvt_pk_bf16_f32 v87, v88, v89
	v_pk_mul_f32 v[168:169], v[90:91], v[172:173] op_sel_hi:[1,0]
	v_pk_mul_f32 v[170:171], v[92:93], v[172:173] op_sel_hi:[1,0]
	v_exp_f32_e32 v168, v168
	v_exp_f32_e32 v169, v169
	v_exp_f32_e32 v170, v170
	v_exp_f32_e32 v171, v171
	v_pk_add_f32 v[168:169], v[168:169], v[174:175] op_sel_hi:[1,0]
	v_pk_add_f32 v[170:171], v[170:171], v[174:175] op_sel_hi:[1,0]
	v_rcp_f32_e32 v168, v168
	v_rcp_f32_e32 v169, v169
	v_rcp_f32_e32 v170, v170
	v_rcp_f32_e32 v171, v171
	v_pk_mul_f32 v[90:91], v[90:91], v[168:169]
	v_pk_mul_f32 v[92:93], v[92:93], v[170:171]
	v_pk_mul_f32 v[82:83], v[82:83], v[90:91]
	v_pk_mul_f32 v[84:85], v[84:85], v[92:93]
	v_cvt_pk_bf16_f32 v88, v82, v83
	v_cvt_pk_bf16_f32 v89, v84, v85
	global_store_dwordx4 v[192:193], v[86:89], off sc1
	v_lshl_add_u64 v[192:193], v[192:193], 0, s[100:101]
	v_pk_mul_f32 v[78:79], v[78:79], v[184:185] op_sel_hi:[1,0]
	v_pk_mul_f32 v[80:81], v[80:81], v[184:185] op_sel_hi:[1,0]
	v_pk_mul_f32 v[74:75], v[74:75], v[184:185] op_sel_hi:[1,0]
	v_pk_mul_f32 v[76:77], v[76:77], v[184:185] op_sel_hi:[1,0]
	v_pk_mul_f32 v[70:71], v[70:71], v[184:185] op_sel_hi:[1,0]
	v_pk_mul_f32 v[72:73], v[72:73], v[184:185] op_sel_hi:[1,0]
	v_pk_mul_f32 v[66:67], v[66:67], v[184:185] op_sel_hi:[1,0]
	v_pk_mul_f32 v[68:69], v[68:69], v[184:185] op_sel_hi:[1,0]
	v_pk_mul_f32 v[168:169], v[78:79], v[172:173] op_sel_hi:[1,0]
	v_pk_mul_f32 v[170:171], v[80:81], v[172:173] op_sel_hi:[1,0]
	v_exp_f32_e32 v168, v168
	v_exp_f32_e32 v169, v169
	v_exp_f32_e32 v170, v170
	v_exp_f32_e32 v171, v171
	v_pk_add_f32 v[168:169], v[168:169], v[174:175] op_sel_hi:[1,0]
	v_pk_add_f32 v[170:171], v[170:171], v[174:175] op_sel_hi:[1,0]
	v_rcp_f32_e32 v168, v168
	v_rcp_f32_e32 v169, v169
	v_rcp_f32_e32 v170, v170
	v_rcp_f32_e32 v171, v171
	v_pk_mul_f32 v[78:79], v[78:79], v[168:169]
	v_pk_mul_f32 v[80:81], v[80:81], v[170:171]
	v_pk_mul_f32 v[70:71], v[70:71], v[78:79]
	v_pk_mul_f32 v[72:73], v[72:73], v[80:81]
	v_cvt_pk_bf16_f32 v70, v70, v71
	v_cvt_pk_bf16_f32 v71, v72, v73
	v_pk_mul_f32 v[168:169], v[74:75], v[172:173] op_sel_hi:[1,0]
	v_pk_mul_f32 v[170:171], v[76:77], v[172:173] op_sel_hi:[1,0]
	v_exp_f32_e32 v168, v168
	v_exp_f32_e32 v169, v169
	v_exp_f32_e32 v170, v170
	v_exp_f32_e32 v171, v171
	v_pk_add_f32 v[168:169], v[168:169], v[174:175] op_sel_hi:[1,0]
	v_pk_add_f32 v[170:171], v[170:171], v[174:175] op_sel_hi:[1,0]
	v_rcp_f32_e32 v168, v168
	v_rcp_f32_e32 v169, v169
	v_rcp_f32_e32 v170, v170
	v_rcp_f32_e32 v171, v171
	v_pk_mul_f32 v[74:75], v[74:75], v[168:169]
	v_pk_mul_f32 v[76:77], v[76:77], v[170:171]
	v_pk_mul_f32 v[66:67], v[66:67], v[74:75]
	v_pk_mul_f32 v[68:69], v[68:69], v[76:77]
	v_cvt_pk_bf16_f32 v72, v66, v67
	v_cvt_pk_bf16_f32 v73, v68, v69
	global_store_dwordx4 v[192:193], v[70:73], off sc1
	v_lshl_add_u64 v[192:193], v[192:193], 0, s[98:99]
	v_pk_mul_f32 v[62:63], v[62:63], v[186:187] op_sel_hi:[1,0]
	v_pk_mul_f32 v[64:65], v[64:65], v[186:187] op_sel_hi:[1,0]
	v_pk_mul_f32 v[58:59], v[58:59], v[186:187] op_sel_hi:[1,0]
; __device__ __forceinline__ unsigned cvt_pk_bf16(float lo, float hi) { unsigned r; asm volatile("v_cvt_pk_bf16_f32 %0, %1, %2" : "=v"(r) : "v"(lo), "v"(hi)); return r; }
; __device__ __forceinline__ float silu_f(float g) { return g * __builtin_amdgcn_rcpf(1.0f + __expf(-g)); }
;     __device__ __forceinline__ void operator()(const f32x4 (&acc)[2][2][4][2], const Unit& u, int ui, int wr, int wc, int fr, int fq) const {
;         const int row0 = u.pm * BM + wr * 64 + fr, col0 = u.pn * HALF + wc * 32 + 8 * fq;
; #pragma unroll
;         for (int ai = 0; ai < 2; ++ai)
; #pragma unroll
;             for (int m = 0; m < 4; ++m) {
;                 const int row = row0 + ai * HALF + m * 16;
;                 const float s = rsb[(ui & 1) * 256 + ai * HALF + wr * 64 + m * 16 + fr];
;                 f32x4 g0 = acc[ai][0][m][0] * s, g1 = acc[ai][0][m][1] * s, u0 = acc[ai][1][m][0] * s, u1 = acc[ai][1][m][1] * s;
;                 u32x4 w;
;                 w.x = cvt_pk_bf16(silu_f(g0[0]) * u0[0], silu_f(g0[1]) * u0[1]); w.y = cvt_pk_bf16(silu_f(g0[2]) * u0[2], silu_f(g0[3]) * u0[3]);
;                 w.z = cvt_pk_bf16(silu_f(g1[0]) * u1[0], silu_f(g1[1]) * u1[1]); w.w = cvt_pk_bf16(silu_f(g1[2]) * u1[2], silu_f(g1[3]) * u1[3]);
;                 *(u32x4*)(H + (size_t)row * ldh + col0) = w;
	v_pk_mul_f32 v[60:61], v[60:61], v[186:187] op_sel_hi:[1,0]
	v_pk_mul_f32 v[54:55], v[54:55], v[186:187] op_sel_hi:[1,0]
	v_pk_mul_f32 v[56:57], v[56:57], v[186:187] op_sel_hi:[1,0]
	v_pk_mul_f32 v[50:51], v[50:51], v[186:187] op_sel_hi:[1,0]
	v_pk_mul_f32 v[52:53], v[52:53], v[186:187] op_sel_hi:[1,0]
	v_pk_mul_f32 v[168:169], v[62:63], v[172:173] op_sel_hi:[1,0]
	v_pk_mul_f32 v[170:171], v[64:65], v[172:173] op_sel_hi:[1,0]
	v_exp_f32_e32 v168, v168
	v_exp_f32_e32 v169, v169
	v_exp_f32_e32 v170, v170
	v_exp_f32_e32 v171, v171
	v_pk_add_f32 v[168:169], v[168:169], v[174:175] op_sel_hi:[1,0]
	v_pk_add_f32 v[170:171], v[170:171], v[174:175] op_sel_hi:[1,0]
	v_rcp_f32_e32 v168, v168
	v_rcp_f32_e32 v169, v169
	v_rcp_f32_e32 v170, v170
	v_rcp_f32_e32 v171, v171
	v_pk_mul_f32 v[62:63], v[62:63], v[168:169]
	v_pk_mul_f32 v[64:65], v[64:65], v[170:171]
	v_pk_mul_f32 v[54:55], v[54:55], v[62:63]
	v_pk_mul_f32 v[56:57], v[56:57], v[64:65]
	v_cvt_pk_bf16_f32 v54, v54, v55
	v_cvt_pk_bf16_f32 v55, v56, v57
	v_pk_mul_f32 v[168:169], v[58:59], v[172:173] op_sel_hi:[1,0]
	v_pk_mul_f32 v[170:171], v[60:61], v[172:173] op_sel_hi:[1,0]
	v_exp_f32_e32 v168, v168
	v_exp_f32_e32 v169, v169
	v_exp_f32_e32 v170, v170
	v_exp_f32_e32 v171, v171
	v_pk_add_f32 v[168:169], v[168:169], v[174:175] op_sel_hi:[1,0]
	v_pk_add_f32 v[170:171], v[170:171], v[174:175] op_sel_hi:[1,0]
	v_rcp_f32_e32 v168, v168
	v_rcp_f32_e32 v169, v169
	v_rcp_f32_e32 v170, v170
	v_rcp_f32_e32 v171, v171
	v_pk_mul_f32 v[58:59], v[58:59], v[168:169]
	v_pk_mul_f32 v[60:61], v[60:61], v[170:171]
	v_pk_mul_f32 v[50:51], v[50:51], v[58:59]
	v_pk_mul_f32 v[52:53], v[52:53], v[60:61]
	v_cvt_pk_bf16_f32 v56, v50, v51
	v_cvt_pk_bf16_f32 v57, v52, v53
	global_store_dwordx4 v[192:193], v[54:57], off sc1
	v_lshl_add_u64 v[192:193], v[192:193], 0, s[98:99]
	v_pk_mul_f32 v[46:47], v[46:47], v[188:189] op_sel_hi:[1,0]
	v_pk_mul_f32 v[48:49], v[48:49], v[188:189] op_sel_hi:[1,0]
	v_pk_mul_f32 v[42:43], v[42:43], v[188:189] op_sel_hi:[1,0]
	v_pk_mul_f32 v[44:45], v[44:45], v[188:189] op_sel_hi:[1,0]
	v_pk_mul_f32 v[38:39], v[38:39], v[188:189] op_sel_hi:[1,0]
	v_pk_mul_f32 v[40:41], v[40:41], v[188:189] op_sel_hi:[1,0]
	v_pk_mul_f32 v[34:35], v[34:35], v[188:189] op_sel_hi:[1,0]
	v_pk_mul_f32 v[36:37], v[36:37], v[188:189] op_sel_hi:[1,0]
	v_pk_mul_f32 v[168:169], v[46:47], v[172:173] op_sel_hi:[1,0]
	v_pk_mul_f32 v[170:171], v[48:49], v[172:173] op_sel_hi:[1,0]
	v_exp_f32_e32 v168, v168
	v_exp_f32_e32 v169, v169
	v_exp_f32_e32 v170, v170
	v_exp_f32_e32 v171, v171
	v_pk_add_f32 v[168:169], v[168:169], v[174:175] op_sel_hi:[1,0]
	v_pk_add_f32 v[170:171], v[170:171], v[174:175] op_sel_hi:[1,0]
	v_rcp_f32_e32 v168, v168
	v_rcp_f32_e32 v169, v169
	v_rcp_f32_e32 v170, v170
	v_rcp_f32_e32 v171, v171
	v_pk_mul_f32 v[46:47], v[46:47], v[168:169]
	v_pk_mul_f32 v[48:49], v[48:49], v[170:171]
	v_pk_mul_f32 v[38:39], v[38:39], v[46:47]
	v_pk_mul_f32 v[40:41], v[40:41], v[48:49]
	v_cvt_pk_bf16_f32 v38, v38, v39
	v_cvt_pk_bf16_f32 v39, v40, v41
	v_pk_mul_f32 v[168:169], v[42:43], v[172:173] op_sel_hi:[1,0]
	v_pk_mul_f32 v[170:171], v[44:45], v[172:173] op_sel_hi:[1,0]
	v_exp_f32_e32 v168, v168
	v_exp_f32_e32 v169, v169
	v_exp_f32_e32 v170, v170
	v_exp_f32_e32 v171, v171
	v_pk_add_f32 v[168:169], v[168:169], v[174:175] op_sel_hi:[1,0]
	v_pk_add_f32 v[170:171], v[170:171], v[174:175] op_sel_hi:[1,0]
	v_rcp_f32_e32 v168, v168
	v_rcp_f32_e32 v169, v169
	v_rcp_f32_e32 v170, v170
	v_rcp_f32_e32 v171, v171
	v_pk_mul_f32 v[42:43], v[42:43], v[168:169]
	v_pk_mul_f32 v[44:45], v[44:45], v[170:171]
	v_pk_mul_f32 v[34:35], v[34:35], v[42:43]
	v_pk_mul_f32 v[36:37], v[36:37], v[44:45]
	v_cvt_pk_bf16_f32 v40, v34, v35
	v_cvt_pk_bf16_f32 v41, v36, v37
	global_store_dwordx4 v[192:193], v[38:41], off sc1
	v_lshl_add_u64 v[192:193], v[192:193], 0, s[98:99]
	v_pk_mul_f32 v[30:31], v[30:31], v[190:191] op_sel_hi:[1,0]
	v_pk_mul_f32 v[32:33], v[32:33], v[190:191] op_sel_hi:[1,0]
	v_pk_mul_f32 v[26:27], v[26:27], v[190:191] op_sel_hi:[1,0]
	v_pk_mul_f32 v[28:29], v[28:29], v[190:191] op_sel_hi:[1,0]
	v_pk_mul_f32 v[22:23], v[22:23], v[190:191] op_sel_hi:[1,0]
	v_pk_mul_f32 v[24:25], v[24:25], v[190:191] op_sel_hi:[1,0]
	v_pk_mul_f32 v[18:19], v[18:19], v[190:191] op_sel_hi:[1,0]
	v_pk_mul_f32 v[20:21], v[20:21], v[190:191] op_sel_hi:[1,0]
	v_pk_mul_f32 v[168:169], v[30:31], v[172:173] op_sel_hi:[1,0]
	v_pk_mul_f32 v[170:171], v[32:33], v[172:173] op_sel_hi:[1,0]
	v_exp_f32_e32 v168, v168
	v_exp_f32_e32 v169, v169
	v_exp_f32_e32 v170, v170
	v_exp_f32_e32 v171, v171
	v_pk_add_f32 v[168:169], v[168:169], v[174:175] op_sel_hi:[1,0]
	v_pk_add_f32 v[170:171], v[170:171], v[174:175] op_sel_hi:[1,0]
	v_rcp_f32_e32 v168, v168
	v_rcp_f32_e32 v169, v169
	v_rcp_f32_e32 v170, v170
	v_rcp_f32_e32 v171, v171
	v_pk_mul_f32 v[30:31], v[30:31], v[168:169]
	v_pk_mul_f32 v[32:33], v[32:33], v[170:171]
	v_pk_mul_f32 v[22:23], v[22:23], v[30:31]
	v_pk_mul_f32 v[24:25], v[24:25], v[32:33]
	v_cvt_pk_bf16_f32 v22, v22, v23
	v_cvt_pk_bf16_f32 v23, v24, v25
	v_pk_mul_f32 v[168:169], v[26:27], v[172:173] op_sel_hi:[1,0]
	v_pk_mul_f32 v[170:171], v[28:29], v[172:173] op_sel_hi:[1,0]
	v_exp_f32_e32 v168, v168
	v_exp_f32_e32 v169, v169
	v_exp_f32_e32 v170, v170
	v_exp_f32_e32 v171, v171
	v_pk_add_f32 v[168:169], v[168:169], v[174:175] op_sel_hi:[1,0]
	v_pk_add_f32 v[170:171], v[170:171], v[174:175] op_sel_hi:[1,0]
	v_rcp_f32_e32 v168, v168
	v_rcp_f32_e32 v169, v169
	v_rcp_f32_e32 v170, v170
	v_rcp_f32_e32 v171, v171
	v_pk_mul_f32 v[26:27], v[26:27], v[168:169]
	v_pk_mul_f32 v[28:29], v[28:29], v[170:171]
	v_pk_mul_f32 v[18:19], v[18:19], v[26:27]
	v_pk_mul_f32 v[20:21], v[20:21], v[28:29]
	v_cvt_pk_bf16_f32 v24, v18, v19
	v_cvt_pk_bf16_f32 v25, v20, v21
	s_mov_b64 s[2:3], -1
	s_cmp_eq_u32 s61, 10
	global_store_dwordx4 v[192:193], v[22:25], off sc1
	s_cbranch_scc1 .LBB0_117
;     static __device__ __forceinline__ float fin(const f32x4& a, const f32x4& b, const f32x4& c, const f32x4& d) {
;         const float s = (((a[0] + a[1]) + (a[2] + a[3])) + ((b[0] + b[1]) + (b[2] + b[3]))) + (((c[0] + c[1]) + (c[2] + c[3])) + ((d[0] + d[1]) + (d[2] + d[3])));
;         return 1.0f / sqrtf(s * (1.0f / 1024.0f) + 1e-6f); }
;     __device__ __forceinline__ void issue(const Unit& u, Pre& p) const {
;         int t = threadIdx.x; asm volatile("" : "+v"(t));
;         if (t < 256) { gp_t g = (gp_t)(ssq + (size_t)(u.pm * BM + t) * 16); p.a = g[0]; p.b = g[1]; p.c = g[2]; p.d = g[3]; }
;     }
;     __device__ __forceinline__ void commit(const Unit& u, int ui, const Pre& p) const {
;         int t = threadIdx.x; asm volatile("" : "+v"(t));
;         if (t < 256) rsb[(ui & 1) * 256 + t] = fin(p.a, p.b, p.c, p.d);
	s_nop 0
	v_add_u32_e32 v18, 0xffffff00, v204
	s_nop 0
	v_cmp_gt_u32_e32 vcc, s68, v18
	s_and_saveexec_b64 s[20:21], vcc
	s_cbranch_execz .LBB0_131
	s_waitcnt vmcnt(8)
	v_mov_b32_e32 v20, v6
	v_mov_b32_e32 v21, v14
	v_mov_b32_e32 v22, v7
	v_mov_b32_e32 v23, v15
	v_pk_add_f32 v[20:21], v[20:21], v[22:23]
	v_mov_b32_e32 v22, v8
	v_mov_b32_e32 v23, v16
	v_mov_b32_e32 v24, v9
	v_mov_b32_e32 v25, v17
	v_pk_add_f32 v[22:23], v[22:23], v[24:25]
	v_mov_b32_e32 v24, v3
	v_pk_add_f32 v[20:21], v[20:21], v[22:23]
	v_mov_b32_e32 v22, v2
	v_mov_b32_e32 v23, v10
	v_mov_b32_e32 v25, v11
	v_pk_add_f32 v[22:23], v[22:23], v[24:25]
	v_mov_b32_e32 v24, v4
	v_mov_b32_e32 v25, v12
	v_mov_b32_e32 v26, v5
	v_mov_b32_e32 v27, v13
	v_pk_add_f32 v[24:25], v[24:25], v[26:27]
	s_nop 0
	v_pk_add_f32 v[22:23], v[22:23], v[24:25]
	s_nop 0
	v_pk_add_f32 v[20:21], v[22:23], v[20:21]
	s_nop 0
	v_add_f32_e32 v19, v20, v21
	v_fmamk_f32 v19, v19, 0x3a800000, v205
	v_mul_f32_e32 v20, 0x4f800000, v19
	v_cmp_gt_f32_e32 vcc, s69, v19
	s_nop 1
	v_cndmask_b32_e32 v19, v19, v20, vcc
	v_sqrt_f32_e32 v20, v19
	s_nop 0
	v_add_u32_e32 v21, -1, v20
	v_fma_f32 v22, -v21, v20, v19
	v_cmp_ge_f32_e64 s[2:3], 0, v22
	v_add_u32_e32 v22, 1, v20
	s_nop 0
	v_cndmask_b32_e64 v21, v20, v21, s[2:3]
	v_fma_f32 v20, -v22, v20, v19
	v_cmp_lt_f32_e64 s[2:3], 0, v20
	s_nop 1
	v_cndmask_b32_e64 v20, v21, v22, s[2:3]
	v_mul_f32_e32 v21, 0x37800000, v20
	v_cndmask_b32_e32 v20, v20, v21, vcc
	v_cmp_class_f32_e32 vcc, v19, v206
	s_nop 1
	v_cndmask_b32_e32 v19, v20, v19, vcc
	v_div_scale_f32 v20, s[2:3], v19, v19, 1.0
	v_rcp_f32_e32 v21, v20
	s_lshl_b32 s2, s60, 10
	s_and_b32 s2, s2, 0x400
	s_add_i32 s2, s2, 0
	v_fma_f32 v22, -v20, v21, 1.0
	v_fmac_f32_e32 v21, v22, v21
	v_div_scale_f32 v22, vcc, 1.0, v19, 1.0
	v_mul_f32_e32 v23, v22, v21
	v_fma_f32 v24, -v20, v23, v22
	v_fmac_f32_e32 v23, v24, v21
	v_fma_f32 v20, -v20, v23, v22
	v_div_fmas_f32 v20, v20, v21, v23
	v_lshl_add_u32 v18, v18, 2, s2
	v_div_fixup_f32 v19, v20, v19, 1.0
	v_add_u32_e32 v18, 0x20400, v18
	ds_write_b32 v18, v19

; __device__ __forceinline__ unsigned cvt_pk_bf16(float lo, float hi) { unsigned r; asm volatile("v_cvt_pk_bf16_f32 %0, %1, %2" : "=v"(r) : "v"(lo), "v"(hi)); return r; }
; __device__ __forceinline__ void resid_bf16_row(const f32x4& a0, const f32x4& a1, float scale, bf16_t* p, const u32x4 w, float& s) {
;     f32x4 o0, o1;
;     o0[0] = __uint_as_float(w.x << 16) + a0[0] * scale; o0[1] = __uint_as_float(w.x & 0xffff0000u) + a0[1] * scale; o0[2] = __uint_as_float(w.y << 16) + a0[2] * scale; o0[3] = __uint_as_float(w.y & 0xffff0000u) + a0[3] * scale;
;     o1[0] = __uint_as_float(w.z << 16) + a1[0] * scale; o1[1] = __uint_as_float(w.z & 0xffff0000u) + a1[1] * scale; o1[2] = __uint_as_float(w.w << 16) + a1[2] * scale; o1[3] = __uint_as_float(w.w & 0xffff0000u) + a1[3] * scale;
;     u32x4 r; r.x = cvt_pk_bf16(o0[0], o0[1]); r.y = cvt_pk_bf16(o0[2], o0[3]); r.z = cvt_pk_bf16(o1[0], o1[1]); r.w = cvt_pk_bf16(o1[2], o1[3]);
;     *(u32x4*)p = r;
;     const float q0 = __uint_as_float(r.x << 16), q1 = __uint_as_float(r.x & 0xffff0000u), q2 = __uint_as_float(r.y << 16), q3 = __uint_as_float(r.y & 0xffff0000u);
;     const float q4 = __uint_as_float(r.z << 16), q5 = __uint_as_float(r.z & 0xffff0000u), q6 = __uint_as_float(r.w << 16), q7 = __uint_as_float(r.w & 0xffff0000u);
;     s += ((q0 * q0 + q1 * q1) + (q2 * q2 + q3 * q3)) + ((q4 * q4 + q5 * q5) + (q6 * q6 + q7 * q7));
;     __device__ __forceinline__ void operator()(const f32x4 (&acc)[2][2][4][2], const Unit& u, int ui, int wr, int wc, int fr, int fq) const {
;     ...
;             for (int m = 0; m < 4; ++m) {
;                 const int row = row0 + ai * HALF + m * 16; bf16_t* p = xb + (size_t)row * ldc + col0; float s = 0.f;
;                 const float scale = rsb[(ui & 1) * 256 + ai * HALF + wr * 64 + m * 16 + fr];
;                 resid_bf16_row(acc[ai][0][m][0], acc[ai][0][m][1], scale, p, old[m][0], s); resid_bf16_row(acc[ai][1][m][0], acc[ai][1][m][1], scale, p + HALF, old[m][1], s);
;                 s = xsum_fq(s);
;                 if (fq == 0) ssq[(size_t)row * 16 + u.pn * 4 + wc] = s;
.LBB0_662:
	s_or_b64 exec, exec, s[2:3]
	ds_read_b32 v3, v1 offset:192
	v_lshlrev_b32_e32 v100, 16, v152
	v_and_b32_e32 v101, 0xffff0000, v152
	v_lshlrev_b32_e32 v102, 16, v153
	v_and_b32_e32 v103, 0xffff0000, v155
	s_waitcnt lgkmcnt(0)
	v_fmac_f32_e32 v100, v96, v3
	v_fmac_f32_e32 v101, v97, v3
	v_fmac_f32_e32 v102, v98, v3
	v_and_b32_e32 v96, 0xffff0000, v153
	v_lshlrev_b32_e32 v97, 16, v154
	v_and_b32_e32 v98, 0xffff0000, v154
	v_fmac_f32_e32 v96, v99, v3
	v_fmac_f32_e32 v97, v92, v3
	v_fmac_f32_e32 v98, v93, v3
	v_lshlrev_b32_e32 v99, 16, v155
	v_cvt_pk_bf16_f32 v92, v100, v101
	v_cvt_pk_bf16_f32 v93, v102, v96
	v_fmac_f32_e32 v99, v94, v3
	v_fmac_f32_e32 v103, v95, v3
	v_cvt_pk_bf16_f32 v94, v97, v98
	v_cvt_pk_bf16_f32 v95, v99, v103
	global_store_dwordx4 v[192:193], v[92:95], off sc1
	v_lshlrev_b32_e32 v96, 16, v92
	v_lshlrev_b32_e32 v97, 16, v93
	v_and_b32_e32 v92, 0xffff0000, v92
	v_and_b32_e32 v93, 0xffff0000, v93
	v_mul_f32_e32 v92, v92, v92
	v_mul_f32_e32 v93, v93, v93
	v_lshlrev_b32_e32 v98, 16, v94
	v_and_b32_e32 v94, 0xffff0000, v94
	v_lshlrev_b32_e32 v99, 16, v95
	v_and_b32_e32 v95, 0xffff0000, v95
	v_fmac_f32_e32 v92, v96, v96
	v_fmac_f32_e32 v93, v97, v97
	v_add_f32_e32 v92, v92, v93
	v_mul_f32_e32 v93, v94, v94
	v_mul_f32_e32 v94, v95, v95
	v_fmac_f32_e32 v93, v98, v98
	v_fmac_f32_e32 v94, v99, v99
	v_add_f32_e32 v93, v93, v94
	v_add_f32_e32 v92, v92, v93
	v_lshlrev_b32_e32 v93, 16, v148
	v_fmac_f32_e32 v93, v88, v3
	v_and_b32_e32 v88, 0xffff0000, v148
	v_fmac_f32_e32 v88, v89, v3
	v_lshlrev_b32_e32 v89, 16, v149
	v_fmac_f32_e32 v89, v90, v3
	v_and_b32_e32 v90, 0xffff0000, v149
	v_fmac_f32_e32 v90, v91, v3
	v_lshlrev_b32_e32 v91, 16, v150
	v_fmac_f32_e32 v91, v84, v3
	v_and_b32_e32 v94, 0xffff0000, v150
	v_lshlrev_b32_e32 v95, 16, v151
	v_and_b32_e32 v96, 0xffff0000, v151
	v_cvt_pk_bf16_f32 v84, v93, v88
	v_fmac_f32_e32 v94, v85, v3
	v_and_b32_e32 v88, 0xffff0000, v84
	v_fmac_f32_e32 v95, v86, v3
	v_fmac_f32_e32 v96, v87, v3
	v_cvt_pk_bf16_f32 v85, v89, v90
	v_lshlrev_b32_e32 v3, 16, v84
	v_and_b32_e32 v90, 0xffff0000, v85
	v_mul_f32_e32 v88, v88, v88
	v_lshlrev_b32_e32 v89, 16, v85
	v_fmac_f32_e32 v88, v3, v3
	v_mul_f32_e32 v3, v90, v90
	v_cvt_pk_bf16_f32 v86, v91, v94
	v_cvt_pk_bf16_f32 v87, v95, v96
	v_fmac_f32_e32 v3, v89, v89
	v_and_b32_e32 v93, 0xffff0000, v86
	v_and_b32_e32 v95, 0xffff0000, v87
	v_lshlrev_b32_e32 v91, 16, v86
	v_lshlrev_b32_e32 v94, 16, v87
	v_add_f32_e32 v3, v88, v3
	v_mul_f32_e32 v88, v93, v93
	v_mul_f32_e32 v89, v95, v95
	v_fmac_f32_e32 v88, v91, v91
	v_fmac_f32_e32 v89, v94, v94
	v_add_f32_e32 v88, v88, v89
	v_add_f32_e32 v3, v3, v88
	v_add_f32_e32 v3, v92, v3
	ds_swizzle_b32 v88, v3 offset:swizzle(SWAP,16)
	global_store_dwordx4 v[192:193], v[84:87], off offset:256
	s_waitcnt lgkmcnt(0)
	v_add_f32_e32 v3, v3, v88
	v_mov_b32_e32 v84, v3
	s_nop 1
	v_permlane32_swap_b32_e32 v3, v84
	s_and_saveexec_b64 s[2:3], s[4:5]
	s_cbranch_execz .LBB0_664
	v_lshlrev_b64 v[86:87], 6, v[190:191]
	v_lshl_add_u64 v[86:87], s[20:21], 0, v[86:87]
	v_add_f32_e32 v3, v3, v84
	global_store_dword v[86:87], v3, off
